# leading-half static prio 1 during resid, kvb and qb-lean epilogues too
# baseline (speedup 1.0000x reference)
; __device__ __forceinline__ u32x4 pack8(const f32x4& a, const f32x4& b, float sc) { u32x4 w; w[0] = pk2(a[0] * sc, a[1] * sc); w[1] = pk2(a[2] * sc, a[3] * sc); w[2] = pk2(b[0] * sc, b[1] * sc); w[3] = pk2(b[2] * sc, b[3] * sc); return w; }
; __device__ __forceinline__ void epi_kvb(const MixBufs B, const f32x4 (&acc)[2][2][4][2], const Unit& u, int wr, int wc, int fr, int fq) {
;     const int pn = u.pn, c8 = wc * 32 + fq * 8;
;     bf16_t* dst = pn < 4 ? mKM(B) : mVM(B); const int hp = pn & 3;
;     f32x4 sq[2];
;     sq[0] = *(const f32x4*)(mSSKV(B) + (size_t)opaque(EPI_ROW(0)) * 4);
; #pragma unroll
;     for (int it = 0; it < 8; ++it) {
;         const int ai = it >> 2, m = it & 3; const int r = opaque(EPI_ROW(it));
;         if (it + 1 < 8) sq[(it + 1) & 1] = *(const f32x4*)(mSSKV(B) + (size_t)opaque(EPI_ROW(it + 1)) * 4);
;         const f32x4 sv = sq[it & 1];
;         const float rs = rsqrtf(((sv[0] + sv[1]) + (sv[2] + sv[3])) * (1.0f / 256) + RMS_EPS);
;         *(u32x4*)(dst + (size_t)r * 1024 + (2 * hp) * 128 + c8) = pack8(acc[ai][0][m][0], acc[ai][0][m][1], rs);
;         *(u32x4*)(dst + (size_t)r * 1024 + (2 * hp + 1) * 128 + c8) = pack8(acc[ai][1][m][0], acc[ai][1][m][1], rs);
;         asm volatile("" ::: "memory");
;     }
; }
.LBB0_520:
	s_lshl_b32 s2, s30, 10
	s_and_b32 s2, s2, 0x400
	s_add_i32 s39, s2, 0
	s_add_i32 s39, s39, 0x20000
	s_cmp_lt_i32 s88, 2
	s_mov_b64 s[2:3], -1
	s_cbranch_scc1 .LBB0_733
	s_cmp_lt_i32 s88, 3
	s_cbranch_scc1 .LBB0_579
	s_cmp_lg_u32 s88, 3
	s_cbranch_scc0 .LBB0_524
	s_cmp_lt_i32 s77, 4
	s_mov_b32 s12, 0x93c1000
	s_mov_b64 s[2:3], s[96:97]
	s_cselect_b32 s12, s12, 0xb3c1000
	s_add_u32 s12, s2, s12
	s_addc_u32 s13, s3, 0
	s_add_u32 s14, s2, 0x19680000
	s_addc_u32 s15, s3, 0
	s_lshl_b32 s16, s81, 8
	s_lshl_b32 s2, s77, 9
	s_and_b32 s2, s2, 0x600
	s_add_u32 s2, s12, s2
	s_addc_u32 s3, s13, 0
	s_add_u32 s2, s2, 0x17e00000
	s_addc_u32 s3, s3, 0
	s_waitcnt lgkmcnt(0)
	v_add_u32_e32 v130, s16, v193
	v_readlane_b32 s12, v254, 34
	v_readlane_b32 s13, v254, 35
	s_and_b64 vcc, exec, s[12:13]
	s_cbranch_vccz .Lkv_noprio
	s_setprio 1
.Lkv_noprio:
	v_lshlrev_b32_e32 v131, 4, v130
	v_lshlrev_b32_e32 v130, 11, v130
	v_lshl_add_u32 v130, v194, 1, v130
	global_load_dwordx4 v[132:135], v131, s[14:15]
	global_load_dwordx4 v[136:139], v131, s[14:15] offset:256
	global_load_dwordx4 v[140:143], v131, s[14:15] offset:512
	global_load_dwordx4 v[144:147], v131, s[14:15] offset:768
	global_load_dwordx4 v[148:151], v131, s[14:15] offset:2048
	global_load_dwordx4 v[152:155], v131, s[14:15] offset:2304
	global_load_dwordx4 v[156:159], v131, s[14:15] offset:2560
	global_load_dwordx4 v[160:163], v131, s[14:15] offset:2816
	s_waitcnt vmcnt(7)
	v_add_f32_e32 v164, v132, v133
	v_add_f32_e32 v165, v134, v135
	v_add_f32_e32 v164, v164, v165
	v_fmamk_f32 v164, v164, 0x3b800000, v222
	v_mul_f32_e32 v165, 0x4b800000, v164
	v_cmp_gt_f32_e32 vcc, s92, v164
	s_nop 1
	v_cndmask_b32_e32 v164, v164, v165, vcc
	v_rsq_f32_e32 v164, v164
	s_nop 0
	v_mul_f32_e32 v165, 0x45800000, v164
	v_cndmask_b32_e32 v166, v164, v165, vcc
	v_pk_mul_f32 v[126:127], v[126:127], v[166:167] op_sel_hi:[1,0]
	v_pk_mul_f32 v[128:129], v[128:129], v[166:167] op_sel_hi:[1,0]
	v_pk_mul_f32 v[118:119], v[118:119], v[166:167] op_sel_hi:[1,0]
	v_pk_mul_f32 v[120:121], v[120:121], v[166:167] op_sel_hi:[1,0]
	v_cvt_pk_bf16_f32 v168, v126, v127
	v_cvt_pk_bf16_f32 v169, v128, v129
	v_cvt_pk_bf16_f32 v170, v118, v119
	v_cvt_pk_bf16_f32 v171, v120, v121
	global_store_dwordx4 v130, v[168:171], s[2:3]
	v_pk_mul_f32 v[122:123], v[122:123], v[166:167] op_sel_hi:[1,0]
	v_pk_mul_f32 v[124:125], v[124:125], v[166:167] op_sel_hi:[1,0]
	v_pk_mul_f32 v[114:115], v[114:115], v[166:167] op_sel_hi:[1,0]
	v_pk_mul_f32 v[116:117], v[116:117], v[166:167] op_sel_hi:[1,0]
	v_cvt_pk_bf16_f32 v172, v122, v123
	v_cvt_pk_bf16_f32 v173, v124, v125
	v_cvt_pk_bf16_f32 v174, v114, v115
	v_cvt_pk_bf16_f32 v175, v116, v117
	global_store_dwordx4 v130, v[172:175], s[2:3] offset:256
	s_waitcnt vmcnt(8)
	v_add_f32_e32 v164, v136, v137
	v_add_f32_e32 v165, v138, v139
	v_add_f32_e32 v164, v164, v165
	v_fmamk_f32 v164, v164, 0x3b800000, v222
	v_mul_f32_e32 v165, 0x4b800000, v164
	v_cmp_gt_f32_e32 vcc, s92, v164
	s_nop 1
	v_cndmask_b32_e32 v164, v164, v165, vcc
	v_rsq_f32_e32 v164, v164
	s_nop 0
	v_mul_f32_e32 v165, 0x45800000, v164
	v_cndmask_b32_e32 v166, v164, v165, vcc
	v_add_u32_e32 v131, 0x8000, v130
	v_pk_mul_f32 v[110:111], v[110:111], v[166:167] op_sel_hi:[1,0]
	v_pk_mul_f32 v[112:113], v[112:113], v[166:167] op_sel_hi:[1,0]
	v_pk_mul_f32 v[102:103], v[102:103], v[166:167] op_sel_hi:[1,0]
	v_pk_mul_f32 v[104:105], v[104:105], v[166:167] op_sel_hi:[1,0]
	v_cvt_pk_bf16_f32 v176, v110, v111
	v_cvt_pk_bf16_f32 v177, v112, v113
	v_cvt_pk_bf16_f32 v178, v102, v103
	v_cvt_pk_bf16_f32 v179, v104, v105
	global_store_dwordx4 v131, v[176:179], s[2:3]
	v_pk_mul_f32 v[106:107], v[106:107], v[166:167] op_sel_hi:[1,0]
	v_pk_mul_f32 v[108:109], v[108:109], v[166:167] op_sel_hi:[1,0]
	v_pk_mul_f32 v[98:99], v[98:99], v[166:167] op_sel_hi:[1,0]
	v_pk_mul_f32 v[100:101], v[100:101], v[166:167] op_sel_hi:[1,0]
	v_cvt_pk_bf16_f32 v200, v106, v107
	v_cvt_pk_bf16_f32 v201, v108, v109
	v_cvt_pk_bf16_f32 v202, v98, v99
	v_cvt_pk_bf16_f32 v203, v100, v101
	global_store_dwordx4 v131, v[200:203], s[2:3] offset:256
	s_waitcnt vmcnt(9)
	v_add_f32_e32 v164, v140, v141
	v_add_f32_e32 v165, v142, v143
	v_add_f32_e32 v164, v164, v165
	v_fmamk_f32 v164, v164, 0x3b800000, v222
	v_mul_f32_e32 v165, 0x4b800000, v164
	v_cmp_gt_f32_e32 vcc, s92, v164
	s_nop 1
	v_cndmask_b32_e32 v164, v164, v165, vcc
	v_rsq_f32_e32 v164, v164
	s_nop 0
	v_mul_f32_e32 v165, 0x45800000, v164
	v_cndmask_b32_e32 v166, v164, v165, vcc
	v_add_u32_e32 v131, 0x10000, v130
	v_pk_mul_f32 v[94:95], v[94:95], v[166:167] op_sel_hi:[1,0]
	v_pk_mul_f32 v[96:97], v[96:97], v[166:167] op_sel_hi:[1,0]
	v_pk_mul_f32 v[86:87], v[86:87], v[166:167] op_sel_hi:[1,0]
	v_pk_mul_f32 v[88:89], v[88:89], v[166:167] op_sel_hi:[1,0]
	v_cvt_pk_bf16_f32 v168, v94, v95
	v_cvt_pk_bf16_f32 v169, v96, v97
	v_cvt_pk_bf16_f32 v170, v86, v87
	v_cvt_pk_bf16_f32 v171, v88, v89
	global_store_dwordx4 v131, v[168:171], s[2:3]
	v_pk_mul_f32 v[90:91], v[90:91], v[166:167] op_sel_hi:[1,0]
	v_pk_mul_f32 v[92:93], v[92:93], v[166:167] op_sel_hi:[1,0]
	v_pk_mul_f32 v[82:83], v[82:83], v[166:167] op_sel_hi:[1,0]
	v_pk_mul_f32 v[84:85], v[84:85], v[166:167] op_sel_hi:[1,0]
	v_cvt_pk_bf16_f32 v172, v90, v91
	v_cvt_pk_bf16_f32 v173, v92, v93
	v_cvt_pk_bf16_f32 v174, v82, v83
	v_cvt_pk_bf16_f32 v175, v84, v85
	global_store_dwordx4 v131, v[172:175], s[2:3] offset:256
	s_waitcnt vmcnt(10)
; __device__ __forceinline__ u32x4 pack8(const f32x4& a, const f32x4& b, float sc) { u32x4 w; w[0] = pk2(a[0] * sc, a[1] * sc); w[1] = pk2(a[2] * sc, a[3] * sc); w[2] = pk2(b[0] * sc, b[1] * sc); w[3] = pk2(b[2] * sc, b[3] * sc); return w; }
; __device__ __forceinline__ void epi_kvb(const MixBufs B, const f32x4 (&acc)[2][2][4][2], const Unit& u, int wr, int wc, int fr, int fq) {
;     ...
;     for (int it = 0; it < 8; ++it) {
;         const int ai = it >> 2, m = it & 3; const int r = opaque(EPI_ROW(it));
;         if (it + 1 < 8) sq[(it + 1) & 1] = *(const f32x4*)(mSSKV(B) + (size_t)opaque(EPI_ROW(it + 1)) * 4);
;         const f32x4 sv = sq[it & 1];
;         const float rs = rsqrtf(((sv[0] + sv[1]) + (sv[2] + sv[3])) * (1.0f / 256) + RMS_EPS);
;         *(u32x4*)(dst + (size_t)r * 1024 + (2 * hp) * 128 + c8) = pack8(acc[ai][0][m][0], acc[ai][0][m][1], rs);
;         *(u32x4*)(dst + (size_t)r * 1024 + (2 * hp + 1) * 128 + c8) = pack8(acc[ai][1][m][0], acc[ai][1][m][1], rs);
;         asm volatile("" ::: "memory");
;     }
	v_add_f32_e32 v164, v144, v145
	v_add_f32_e32 v165, v146, v147
	v_add_f32_e32 v164, v164, v165
	v_fmamk_f32 v164, v164, 0x3b800000, v222
	v_mul_f32_e32 v165, 0x4b800000, v164
	v_cmp_gt_f32_e32 vcc, s92, v164
	s_nop 1
	v_cndmask_b32_e32 v164, v164, v165, vcc
	v_rsq_f32_e32 v164, v164
	s_nop 0
	v_mul_f32_e32 v165, 0x45800000, v164
	v_cndmask_b32_e32 v166, v164, v165, vcc
	v_add_u32_e32 v131, 0x18000, v130
	v_pk_mul_f32 v[78:79], v[78:79], v[166:167] op_sel_hi:[1,0]
	v_pk_mul_f32 v[80:81], v[80:81], v[166:167] op_sel_hi:[1,0]
	v_pk_mul_f32 v[70:71], v[70:71], v[166:167] op_sel_hi:[1,0]
	v_pk_mul_f32 v[72:73], v[72:73], v[166:167] op_sel_hi:[1,0]
	v_cvt_pk_bf16_f32 v176, v78, v79
	v_cvt_pk_bf16_f32 v177, v80, v81
	v_cvt_pk_bf16_f32 v178, v70, v71
	v_cvt_pk_bf16_f32 v179, v72, v73
	global_store_dwordx4 v131, v[176:179], s[2:3]
	v_pk_mul_f32 v[74:75], v[74:75], v[166:167] op_sel_hi:[1,0]
	v_pk_mul_f32 v[76:77], v[76:77], v[166:167] op_sel_hi:[1,0]
	v_pk_mul_f32 v[66:67], v[66:67], v[166:167] op_sel_hi:[1,0]
	v_pk_mul_f32 v[68:69], v[68:69], v[166:167] op_sel_hi:[1,0]
	v_cvt_pk_bf16_f32 v200, v74, v75
	v_cvt_pk_bf16_f32 v201, v76, v77
	v_cvt_pk_bf16_f32 v202, v66, v67
	v_cvt_pk_bf16_f32 v203, v68, v69
	global_store_dwordx4 v131, v[200:203], s[2:3] offset:256
	s_waitcnt vmcnt(11)
	v_add_f32_e32 v164, v148, v149
	v_add_f32_e32 v165, v150, v151
	v_add_f32_e32 v164, v164, v165
	v_fmamk_f32 v164, v164, 0x3b800000, v222
	v_mul_f32_e32 v165, 0x4b800000, v164
	v_cmp_gt_f32_e32 vcc, s92, v164
	s_nop 1
	v_cndmask_b32_e32 v164, v164, v165, vcc
	v_rsq_f32_e32 v164, v164
	s_nop 0
	v_mul_f32_e32 v165, 0x45800000, v164
	v_cndmask_b32_e32 v166, v164, v165, vcc
	v_add_u32_e32 v131, 0x40000, v130
	v_pk_mul_f32 v[62:63], v[62:63], v[166:167] op_sel_hi:[1,0]
	v_pk_mul_f32 v[64:65], v[64:65], v[166:167] op_sel_hi:[1,0]
	v_pk_mul_f32 v[54:55], v[54:55], v[166:167] op_sel_hi:[1,0]
	v_pk_mul_f32 v[56:57], v[56:57], v[166:167] op_sel_hi:[1,0]
	v_cvt_pk_bf16_f32 v168, v62, v63
	v_cvt_pk_bf16_f32 v169, v64, v65
	v_cvt_pk_bf16_f32 v170, v54, v55
	v_cvt_pk_bf16_f32 v171, v56, v57
	global_store_dwordx4 v131, v[168:171], s[2:3]
	v_pk_mul_f32 v[58:59], v[58:59], v[166:167] op_sel_hi:[1,0]
	v_pk_mul_f32 v[60:61], v[60:61], v[166:167] op_sel_hi:[1,0]
	v_pk_mul_f32 v[50:51], v[50:51], v[166:167] op_sel_hi:[1,0]
	v_pk_mul_f32 v[52:53], v[52:53], v[166:167] op_sel_hi:[1,0]
	v_cvt_pk_bf16_f32 v172, v58, v59
	v_cvt_pk_bf16_f32 v173, v60, v61
	v_cvt_pk_bf16_f32 v174, v50, v51
	v_cvt_pk_bf16_f32 v175, v52, v53
	global_store_dwordx4 v131, v[172:175], s[2:3] offset:256
	s_waitcnt vmcnt(12)
	v_add_f32_e32 v164, v152, v153
	v_add_f32_e32 v165, v154, v155
	v_add_f32_e32 v164, v164, v165
	v_fmamk_f32 v164, v164, 0x3b800000, v222
	v_mul_f32_e32 v165, 0x4b800000, v164
	v_cmp_gt_f32_e32 vcc, s92, v164
	s_nop 1
	v_cndmask_b32_e32 v164, v164, v165, vcc
	v_rsq_f32_e32 v164, v164
	s_nop 0
	v_mul_f32_e32 v165, 0x45800000, v164
	v_cndmask_b32_e32 v166, v164, v165, vcc
	v_add_u32_e32 v131, 0x48000, v130
	v_pk_mul_f32 v[46:47], v[46:47], v[166:167] op_sel_hi:[1,0]
	v_pk_mul_f32 v[48:49], v[48:49], v[166:167] op_sel_hi:[1,0]
	v_pk_mul_f32 v[38:39], v[38:39], v[166:167] op_sel_hi:[1,0]
	v_pk_mul_f32 v[40:41], v[40:41], v[166:167] op_sel_hi:[1,0]
	v_cvt_pk_bf16_f32 v176, v46, v47
	v_cvt_pk_bf16_f32 v177, v48, v49
	v_cvt_pk_bf16_f32 v178, v38, v39
	v_cvt_pk_bf16_f32 v179, v40, v41
	global_store_dwordx4 v131, v[176:179], s[2:3]
	v_pk_mul_f32 v[42:43], v[42:43], v[166:167] op_sel_hi:[1,0]
	v_pk_mul_f32 v[44:45], v[44:45], v[166:167] op_sel_hi:[1,0]
	v_pk_mul_f32 v[34:35], v[34:35], v[166:167] op_sel_hi:[1,0]
	v_pk_mul_f32 v[36:37], v[36:37], v[166:167] op_sel_hi:[1,0]
	v_cvt_pk_bf16_f32 v200, v42, v43
	v_cvt_pk_bf16_f32 v201, v44, v45
	v_cvt_pk_bf16_f32 v202, v34, v35
	v_cvt_pk_bf16_f32 v203, v36, v37
	global_store_dwordx4 v131, v[200:203], s[2:3] offset:256
	s_waitcnt vmcnt(13)
	v_add_f32_e32 v164, v156, v157
	v_add_f32_e32 v165, v158, v159
	v_add_f32_e32 v164, v164, v165
	v_fmamk_f32 v164, v164, 0x3b800000, v222
	v_mul_f32_e32 v165, 0x4b800000, v164
	v_cmp_gt_f32_e32 vcc, s92, v164
	s_nop 1
	v_cndmask_b32_e32 v164, v164, v165, vcc
	v_rsq_f32_e32 v164, v164
	s_nop 0
	v_mul_f32_e32 v165, 0x45800000, v164
	v_cndmask_b32_e32 v166, v164, v165, vcc
	v_add_u32_e32 v131, 0x50000, v130
	v_pk_mul_f32 v[30:31], v[30:31], v[166:167] op_sel_hi:[1,0]
	v_pk_mul_f32 v[32:33], v[32:33], v[166:167] op_sel_hi:[1,0]
	v_pk_mul_f32 v[22:23], v[22:23], v[166:167] op_sel_hi:[1,0]
	v_pk_mul_f32 v[24:25], v[24:25], v[166:167] op_sel_hi:[1,0]
	v_cvt_pk_bf16_f32 v168, v30, v31
	v_cvt_pk_bf16_f32 v169, v32, v33
	v_cvt_pk_bf16_f32 v170, v22, v23
	v_cvt_pk_bf16_f32 v171, v24, v25
	global_store_dwordx4 v131, v[168:171], s[2:3]
	v_pk_mul_f32 v[26:27], v[26:27], v[166:167] op_sel_hi:[1,0]
	v_pk_mul_f32 v[28:29], v[28:29], v[166:167] op_sel_hi:[1,0]
	v_pk_mul_f32 v[18:19], v[18:19], v[166:167] op_sel_hi:[1,0]
	v_pk_mul_f32 v[20:21], v[20:21], v[166:167] op_sel_hi:[1,0]
	v_cvt_pk_bf16_f32 v172, v26, v27
	v_cvt_pk_bf16_f32 v173, v28, v29
	v_cvt_pk_bf16_f32 v174, v18, v19
	v_cvt_pk_bf16_f32 v175, v20, v21
	global_store_dwordx4 v131, v[172:175], s[2:3] offset:256
	s_waitcnt vmcnt(14)
	v_add_f32_e32 v164, v160, v161
	v_add_f32_e32 v165, v162, v163
	v_add_f32_e32 v164, v164, v165
	v_fmamk_f32 v164, v164, 0x3b800000, v222
	v_mul_f32_e32 v165, 0x4b800000, v164
	v_cmp_gt_f32_e32 vcc, s92, v164
	s_nop 1
	v_cndmask_b32_e32 v164, v164, v165, vcc
	v_rsq_f32_e32 v164, v164
	s_nop 0
	v_mul_f32_e32 v165, 0x45800000, v164
	v_cndmask_b32_e32 v166, v164, v165, vcc
	v_add_u32_e32 v131, 0x58000, v130
	v_pk_mul_f32 v[14:15], v[14:15], v[166:167] op_sel_hi:[1,0]
	v_pk_mul_f32 v[16:17], v[16:17], v[166:167] op_sel_hi:[1,0]
	v_pk_mul_f32 v[6:7], v[6:7], v[166:167] op_sel_hi:[1,0]
	v_pk_mul_f32 v[8:9], v[8:9], v[166:167] op_sel_hi:[1,0]
	v_cvt_pk_bf16_f32 v176, v14, v15
	v_cvt_pk_bf16_f32 v177, v16, v17
	v_cvt_pk_bf16_f32 v178, v6, v7
	v_cvt_pk_bf16_f32 v179, v8, v9
	global_store_dwordx4 v131, v[176:179], s[2:3]
	v_pk_mul_f32 v[10:11], v[10:11], v[166:167] op_sel_hi:[1,0]
	v_pk_mul_f32 v[12:13], v[12:13], v[166:167] op_sel_hi:[1,0]
	v_pk_mul_f32 v[2:3], v[2:3], v[166:167] op_sel_hi:[1,0]
	v_pk_mul_f32 v[4:5], v[4:5], v[166:167] op_sel_hi:[1,0]
	v_cvt_pk_bf16_f32 v200, v10, v11
	v_cvt_pk_bf16_f32 v201, v12, v13
	v_cvt_pk_bf16_f32 v202, v2, v3
	v_cvt_pk_bf16_f32 v203, v4, v5
	global_store_dwordx4 v131, v[200:203], s[2:3] offset:256
	s_setprio 0
	s_mov_b64 s[2:3], 0
; __device__ __forceinline__ u32x4 pack8(const f32x4& a, const f32x4& b, float sc) { u32x4 w; w[0] = pk2(a[0] * sc, a[1] * sc); w[1] = pk2(a[2] * sc, a[3] * sc); w[2] = pk2(b[0] * sc, b[1] * sc); w[3] = pk2(b[2] * sc, b[3] * sc); return w; }
; __device__ __forceinline__ void epi_qb(const MixBufs B, const f32x2* ROPE, const f32x4 (&acc)[2][2][4][2], const Unit& u, int wr, int wc, int fr, int fq) {
;     const int pn = u.pn;
;     const bool roped = pn >= 4;
;     bf16_t* dst = roped ? mQM(B) + ((pn - 4) * 4 + wc) * 192 + 128 : mQM(B) + (2 * pn) * 192 + wc * 32;
;     const int loff = fq * 8;
;     Rope8 R[2]; f32x4 sq[2][2];
;     { const int r0 = opaque(EPI_ROW(0)); if (roped) rope_load(R[0], ROPE, r0, fq * 8); const f32x4* p = (const f32x4*)(mSSQ(B) + (size_t)r0 * 8); sq[0][0] = p[0]; sq[0][1] = p[1]; }
; #pragma unroll
;     for (int it = 0; it < 8; ++it) {
;         const int ai = it >> 2, m = it & 3; const int r = opaque(EPI_ROW(it));
;         if (it + 1 < 8) { const int rn = opaque(EPI_ROW(it + 1)); if (roped) rope_load(R[(it + 1) & 1], ROPE, rn, fq * 8);
;             const f32x4* p = (const f32x4*)(mSSQ(B) + (size_t)rn * 8); sq[(it + 1) & 1][0] = p[0]; sq[(it + 1) & 1][1] = p[1]; }
;         const f32x4 sv = sq[it & 1][0] + sq[it & 1][1];
;         const float rs = rsqrtf(((sv[0] + sv[1]) + (sv[2] + sv[3])) * (1.0f / 512) + RMS_EPS) * QSCALE_M;
;         const f32x4 (&a0)[2] = acc[ai][0][m]; const f32x4 (&a1)[2] = acc[ai][1][m];
;         bf16_t* p = dst + (size_t)r * 1536 + loff;
;         if (!roped) { *(u32x4*)p = pack8(a0[0], a0[1], rs); *(u32x4*)(p + 192) = pack8(a1[0], a1[1], rs); }
;         else { u32x4 w1, w2; rope8(a0, a1, rs, R[it & 1], w1, w2); *(u32x4*)p = w1; *(u32x4*)(p + 32) = w2; }
.LBB0_524:
	s_andn2_b64 vcc, exec, s[2:3]
	s_cbranch_vccnz .LBB0_578
	s_cmp_gt_i32 s77, 3
	s_cbranch_scc1 .Lqb_orig
	s_mov_b64 s[2:3], s[96:97]
	s_mul_i32 s14, s77, 0x300
	v_readlane_b32 s16, v255, 1
	s_lshl_b32 s16, s16, 1
	s_add_i32 s14, s14, s16
	s_add_u32 s12, s2, 0x1e1c1000
	s_addc_u32 s13, s3, 0
	s_add_u32 s12, s12, s14
	s_addc_u32 s13, s13, 0
	s_add_u32 s14, s2, 0x19600000
	s_addc_u32 s15, s3, 0
	s_lshl_b32 s16, s81, 8
	s_waitcnt lgkmcnt(0)
	v_add_u32_e32 v130, s16, v193
	v_readlane_b32 s2, v254, 34
	v_readlane_b32 s3, v254, 35
	s_and_b64 vcc, exec, s[2:3]
	s_cbranch_vccz .Lqb_noprio
	s_setprio 1
.Lqb_noprio:
	v_lshlrev_b32_e32 v246, 5, v130
	v_add_u32_e32 v247, 0x1000, v246
	v_mul_u32_u24_e32 v130, 0xc00, v130
	v_lshl_add_u32 v130, v192, 1, v130
	global_load_dwordx4 v[132:135], v246, s[14:15]
	global_load_dwordx4 v[136:139], v246, s[14:15] offset:16
	global_load_dwordx4 v[140:143], v246, s[14:15] offset:512
	global_load_dwordx4 v[144:147], v246, s[14:15] offset:528
	global_load_dwordx4 v[148:151], v246, s[14:15] offset:1024
	global_load_dwordx4 v[152:155], v246, s[14:15] offset:1040
	global_load_dwordx4 v[156:159], v246, s[14:15] offset:1536
	global_load_dwordx4 v[160:163], v246, s[14:15] offset:1552
	global_load_dwordx4 v[164:167], v247, s[14:15]
	global_load_dwordx4 v[168:171], v247, s[14:15] offset:16
	global_load_dwordx4 v[172:175], v247, s[14:15] offset:512
	global_load_dwordx4 v[176:179], v247, s[14:15] offset:528
	global_load_dwordx4 v[200:203], v247, s[14:15] offset:1024
	global_load_dwordx4 v[204:207], v247, s[14:15] offset:1040
	global_load_dwordx4 v[208:211], v247, s[14:15] offset:1536
	global_load_dwordx4 v[212:215], v247, s[14:15] offset:1552
	s_waitcnt vmcnt(14)
	v_pk_add_f32 v[132:133], v[132:133], v[136:137]
	v_pk_add_f32 v[134:135], v[134:135], v[138:139]
	v_add_f32_e32 v180, v132, v133
	v_add_f32_e32 v181, v134, v135
	v_add_f32_e32 v180, v180, v181
	v_fmamk_f32 v180, v180, 0x3b000000, v222
	v_mul_f32_e32 v181, 0x4b800000, v180
	v_cmp_gt_f32_e32 vcc, s92, v180
	s_nop 1
	v_cndmask_b32_e32 v180, v180, v181, vcc
	v_rsq_f32_e32 v180, v180
	s_nop 0
	v_mul_f32_e32 v181, 0x45800000, v180
	v_cndmask_b32_e32 v180, v180, v181, vcc
	v_mul_f32_e32 v244, 0x3dd53b94, v180
	v_pk_mul_f32 v[126:127], v[126:127], v[244:245] op_sel_hi:[1,0]
	v_pk_mul_f32 v[128:129], v[128:129], v[244:245] op_sel_hi:[1,0]
	v_pk_mul_f32 v[118:119], v[118:119], v[244:245] op_sel_hi:[1,0]
	v_pk_mul_f32 v[120:121], v[120:121], v[244:245] op_sel_hi:[1,0]
	v_cvt_pk_bf16_f32 v132, v126, v127
	v_cvt_pk_bf16_f32 v133, v128, v129
	v_cvt_pk_bf16_f32 v134, v118, v119
	v_cvt_pk_bf16_f32 v135, v120, v121
	global_store_dwordx4 v130, v[132:135], s[12:13]
	v_pk_mul_f32 v[122:123], v[122:123], v[244:245] op_sel_hi:[1,0]
	v_pk_mul_f32 v[124:125], v[124:125], v[244:245] op_sel_hi:[1,0]
	v_pk_mul_f32 v[114:115], v[114:115], v[244:245] op_sel_hi:[1,0]
	v_pk_mul_f32 v[116:117], v[116:117], v[244:245] op_sel_hi:[1,0]
	v_cvt_pk_bf16_f32 v136, v122, v123
	v_cvt_pk_bf16_f32 v137, v124, v125
	v_cvt_pk_bf16_f32 v138, v114, v115
	v_cvt_pk_bf16_f32 v139, v116, v117
	global_store_dwordx4 v130, v[136:139], s[12:13] offset:384
	s_waitcnt vmcnt(14)
	v_pk_add_f32 v[140:141], v[140:141], v[144:145]
	v_pk_add_f32 v[142:143], v[142:143], v[146:147]
	v_add_f32_e32 v180, v140, v141
	v_add_f32_e32 v181, v142, v143
	v_add_f32_e32 v180, v180, v181
	v_fmamk_f32 v180, v180, 0x3b000000, v222
	v_mul_f32_e32 v181, 0x4b800000, v180
	v_cmp_gt_f32_e32 vcc, s92, v180
	s_nop 1
	v_cndmask_b32_e32 v180, v180, v181, vcc
	v_rsq_f32_e32 v180, v180
	s_nop 0
	v_mul_f32_e32 v181, 0x45800000, v180
	v_cndmask_b32_e32 v180, v180, v181, vcc
	v_mul_f32_e32 v244, 0x3dd53b94, v180
	v_add_u32_e32 v131, 0xc000, v130
	v_pk_mul_f32 v[110:111], v[110:111], v[244:245] op_sel_hi:[1,0]
	v_pk_mul_f32 v[112:113], v[112:113], v[244:245] op_sel_hi:[1,0]
	v_pk_mul_f32 v[102:103], v[102:103], v[244:245] op_sel_hi:[1,0]
	v_pk_mul_f32 v[104:105], v[104:105], v[244:245] op_sel_hi:[1,0]
	v_cvt_pk_bf16_f32 v140, v110, v111
	v_cvt_pk_bf16_f32 v141, v112, v113
	v_cvt_pk_bf16_f32 v142, v102, v103
	v_cvt_pk_bf16_f32 v143, v104, v105
	global_store_dwordx4 v131, v[140:143], s[12:13]
	v_pk_mul_f32 v[106:107], v[106:107], v[244:245] op_sel_hi:[1,0]
	v_pk_mul_f32 v[108:109], v[108:109], v[244:245] op_sel_hi:[1,0]
	v_pk_mul_f32 v[98:99], v[98:99], v[244:245] op_sel_hi:[1,0]
	v_pk_mul_f32 v[100:101], v[100:101], v[244:245] op_sel_hi:[1,0]
	v_cvt_pk_bf16_f32 v144, v106, v107
	v_cvt_pk_bf16_f32 v145, v108, v109
	v_cvt_pk_bf16_f32 v146, v98, v99
	v_cvt_pk_bf16_f32 v147, v100, v101
	global_store_dwordx4 v131, v[144:147], s[12:13] offset:384
	s_waitcnt vmcnt(14)
	v_pk_add_f32 v[148:149], v[148:149], v[152:153]
	v_pk_add_f32 v[150:151], v[150:151], v[154:155]
	v_add_f32_e32 v180, v148, v149
	v_add_f32_e32 v181, v150, v151
	v_add_f32_e32 v180, v180, v181
	v_fmamk_f32 v180, v180, 0x3b000000, v222
	v_mul_f32_e32 v181, 0x4b800000, v180
	v_cmp_gt_f32_e32 vcc, s92, v180
	s_nop 1
	v_cndmask_b32_e32 v180, v180, v181, vcc
	v_rsq_f32_e32 v180, v180
	s_nop 0
	v_mul_f32_e32 v181, 0x45800000, v180
	v_cndmask_b32_e32 v180, v180, v181, vcc
	v_mul_f32_e32 v244, 0x3dd53b94, v180
	v_add_u32_e32 v131, 0x18000, v130
	v_pk_mul_f32 v[94:95], v[94:95], v[244:245] op_sel_hi:[1,0]
	v_pk_mul_f32 v[96:97], v[96:97], v[244:245] op_sel_hi:[1,0]
	v_pk_mul_f32 v[86:87], v[86:87], v[244:245] op_sel_hi:[1,0]
	v_pk_mul_f32 v[88:89], v[88:89], v[244:245] op_sel_hi:[1,0]
	v_cvt_pk_bf16_f32 v148, v94, v95
	v_cvt_pk_bf16_f32 v149, v96, v97
	v_cvt_pk_bf16_f32 v150, v86, v87
	v_cvt_pk_bf16_f32 v151, v88, v89
	global_store_dwordx4 v131, v[148:151], s[12:13]
	v_pk_mul_f32 v[90:91], v[90:91], v[244:245] op_sel_hi:[1,0]
	v_pk_mul_f32 v[92:93], v[92:93], v[244:245] op_sel_hi:[1,0]
	v_pk_mul_f32 v[82:83], v[82:83], v[244:245] op_sel_hi:[1,0]
	v_pk_mul_f32 v[84:85], v[84:85], v[244:245] op_sel_hi:[1,0]
	v_cvt_pk_bf16_f32 v152, v90, v91
	v_cvt_pk_bf16_f32 v153, v92, v93
	v_cvt_pk_bf16_f32 v154, v82, v83
	v_cvt_pk_bf16_f32 v155, v84, v85
	global_store_dwordx4 v131, v[152:155], s[12:13] offset:384
	s_waitcnt vmcnt(14)
; __device__ __forceinline__ u32x4 pack8(const f32x4& a, const f32x4& b, float sc) { u32x4 w; w[0] = pk2(a[0] * sc, a[1] * sc); w[1] = pk2(a[2] * sc, a[3] * sc); w[2] = pk2(b[0] * sc, b[1] * sc); w[3] = pk2(b[2] * sc, b[3] * sc); return w; }
; __device__ __forceinline__ void epi_qb(const MixBufs B, const f32x2* ROPE, const f32x4 (&acc)[2][2][4][2], const Unit& u, int wr, int wc, int fr, int fq) {
;     ...
;     for (int it = 0; it < 8; ++it) {
;         const int ai = it >> 2, m = it & 3; const int r = opaque(EPI_ROW(it));
;         if (it + 1 < 8) { const int rn = opaque(EPI_ROW(it + 1)); if (roped) rope_load(R[(it + 1) & 1], ROPE, rn, fq * 8);
;             const f32x4* p = (const f32x4*)(mSSQ(B) + (size_t)rn * 8); sq[(it + 1) & 1][0] = p[0]; sq[(it + 1) & 1][1] = p[1]; }
;         const f32x4 sv = sq[it & 1][0] + sq[it & 1][1];
;         const float rs = rsqrtf(((sv[0] + sv[1]) + (sv[2] + sv[3])) * (1.0f / 512) + RMS_EPS) * QSCALE_M;
;         const f32x4 (&a0)[2] = acc[ai][0][m]; const f32x4 (&a1)[2] = acc[ai][1][m];
;         bf16_t* p = dst + (size_t)r * 1536 + loff;
;         if (!roped) { *(u32x4*)p = pack8(a0[0], a0[1], rs); *(u32x4*)(p + 192) = pack8(a1[0], a1[1], rs); }
;         else { u32x4 w1, w2; rope8(a0, a1, rs, R[it & 1], w1, w2); *(u32x4*)p = w1; *(u32x4*)(p + 32) = w2; }
	v_pk_add_f32 v[156:157], v[156:157], v[160:161]
	v_pk_add_f32 v[158:159], v[158:159], v[162:163]
	v_add_f32_e32 v180, v156, v157
	v_add_f32_e32 v181, v158, v159
	v_add_f32_e32 v180, v180, v181
	v_fmamk_f32 v180, v180, 0x3b000000, v222
	v_mul_f32_e32 v181, 0x4b800000, v180
	v_cmp_gt_f32_e32 vcc, s92, v180
	s_nop 1
	v_cndmask_b32_e32 v180, v180, v181, vcc
	v_rsq_f32_e32 v180, v180
	s_nop 0
	v_mul_f32_e32 v181, 0x45800000, v180
	v_cndmask_b32_e32 v180, v180, v181, vcc
	v_mul_f32_e32 v244, 0x3dd53b94, v180
	v_add_u32_e32 v131, 0x24000, v130
	v_pk_mul_f32 v[78:79], v[78:79], v[244:245] op_sel_hi:[1,0]
	v_pk_mul_f32 v[80:81], v[80:81], v[244:245] op_sel_hi:[1,0]
	v_pk_mul_f32 v[70:71], v[70:71], v[244:245] op_sel_hi:[1,0]
	v_pk_mul_f32 v[72:73], v[72:73], v[244:245] op_sel_hi:[1,0]
	v_cvt_pk_bf16_f32 v156, v78, v79
	v_cvt_pk_bf16_f32 v157, v80, v81
	v_cvt_pk_bf16_f32 v158, v70, v71
	v_cvt_pk_bf16_f32 v159, v72, v73
	global_store_dwordx4 v131, v[156:159], s[12:13]
	v_pk_mul_f32 v[74:75], v[74:75], v[244:245] op_sel_hi:[1,0]
	v_pk_mul_f32 v[76:77], v[76:77], v[244:245] op_sel_hi:[1,0]
	v_pk_mul_f32 v[66:67], v[66:67], v[244:245] op_sel_hi:[1,0]
	v_pk_mul_f32 v[68:69], v[68:69], v[244:245] op_sel_hi:[1,0]
	v_cvt_pk_bf16_f32 v160, v74, v75
	v_cvt_pk_bf16_f32 v161, v76, v77
	v_cvt_pk_bf16_f32 v162, v66, v67
	v_cvt_pk_bf16_f32 v163, v68, v69
	global_store_dwordx4 v131, v[160:163], s[12:13] offset:384
	s_waitcnt vmcnt(14)
	v_pk_add_f32 v[164:165], v[164:165], v[168:169]
	v_pk_add_f32 v[166:167], v[166:167], v[170:171]
	v_add_f32_e32 v180, v164, v165
	v_add_f32_e32 v181, v166, v167
	v_add_f32_e32 v180, v180, v181
	v_fmamk_f32 v180, v180, 0x3b000000, v222
	v_mul_f32_e32 v181, 0x4b800000, v180
	v_cmp_gt_f32_e32 vcc, s92, v180
	s_nop 1
	v_cndmask_b32_e32 v180, v180, v181, vcc
	v_rsq_f32_e32 v180, v180
	s_nop 0
	v_mul_f32_e32 v181, 0x45800000, v180
	v_cndmask_b32_e32 v180, v180, v181, vcc
	v_mul_f32_e32 v244, 0x3dd53b94, v180
	v_add_u32_e32 v131, 0x60000, v130
	v_pk_mul_f32 v[62:63], v[62:63], v[244:245] op_sel_hi:[1,0]
	v_pk_mul_f32 v[64:65], v[64:65], v[244:245] op_sel_hi:[1,0]
	v_pk_mul_f32 v[54:55], v[54:55], v[244:245] op_sel_hi:[1,0]
	v_pk_mul_f32 v[56:57], v[56:57], v[244:245] op_sel_hi:[1,0]
	v_cvt_pk_bf16_f32 v164, v62, v63
	v_cvt_pk_bf16_f32 v165, v64, v65
	v_cvt_pk_bf16_f32 v166, v54, v55
	v_cvt_pk_bf16_f32 v167, v56, v57
	global_store_dwordx4 v131, v[164:167], s[12:13]
	v_pk_mul_f32 v[58:59], v[58:59], v[244:245] op_sel_hi:[1,0]
	v_pk_mul_f32 v[60:61], v[60:61], v[244:245] op_sel_hi:[1,0]
	v_pk_mul_f32 v[50:51], v[50:51], v[244:245] op_sel_hi:[1,0]
	v_pk_mul_f32 v[52:53], v[52:53], v[244:245] op_sel_hi:[1,0]
	v_cvt_pk_bf16_f32 v168, v58, v59
	v_cvt_pk_bf16_f32 v169, v60, v61
	v_cvt_pk_bf16_f32 v170, v50, v51
	v_cvt_pk_bf16_f32 v171, v52, v53
	global_store_dwordx4 v131, v[168:171], s[12:13] offset:384
	s_waitcnt vmcnt(14)
; __device__ __forceinline__ u32x4 pack8(const f32x4& a, const f32x4& b, float sc) { u32x4 w; w[0] = pk2(a[0] * sc, a[1] * sc); w[1] = pk2(a[2] * sc, a[3] * sc); w[2] = pk2(b[0] * sc, b[1] * sc); w[3] = pk2(b[2] * sc, b[3] * sc); return w; }
; __device__ __forceinline__ void epi_qb(const MixBufs B, const f32x2* ROPE, const f32x4 (&acc)[2][2][4][2], const Unit& u, int wr, int wc, int fr, int fq) {
;     ...
;     for (int it = 0; it < 8; ++it) {
;         const int ai = it >> 2, m = it & 3; const int r = opaque(EPI_ROW(it));
;         if (it + 1 < 8) { const int rn = opaque(EPI_ROW(it + 1)); if (roped) rope_load(R[(it + 1) & 1], ROPE, rn, fq * 8);
;             const f32x4* p = (const f32x4*)(mSSQ(B) + (size_t)rn * 8); sq[(it + 1) & 1][0] = p[0]; sq[(it + 1) & 1][1] = p[1]; }
;         const f32x4 sv = sq[it & 1][0] + sq[it & 1][1];
;         const float rs = rsqrtf(((sv[0] + sv[1]) + (sv[2] + sv[3])) * (1.0f / 512) + RMS_EPS) * QSCALE_M;
;         const f32x4 (&a0)[2] = acc[ai][0][m]; const f32x4 (&a1)[2] = acc[ai][1][m];
;         bf16_t* p = dst + (size_t)r * 1536 + loff;
;         if (!roped) { *(u32x4*)p = pack8(a0[0], a0[1], rs); *(u32x4*)(p + 192) = pack8(a1[0], a1[1], rs); }
;         else { u32x4 w1, w2; rope8(a0, a1, rs, R[it & 1], w1, w2); *(u32x4*)p = w1; *(u32x4*)(p + 32) = w2; }
;         asm volatile("" ::: "memory");
	v_pk_add_f32 v[172:173], v[172:173], v[176:177]
	v_pk_add_f32 v[174:175], v[174:175], v[178:179]
	v_add_f32_e32 v180, v172, v173
	v_add_f32_e32 v181, v174, v175
	v_add_f32_e32 v180, v180, v181
	v_fmamk_f32 v180, v180, 0x3b000000, v222
	v_mul_f32_e32 v181, 0x4b800000, v180
	v_cmp_gt_f32_e32 vcc, s92, v180
	s_nop 1
	v_cndmask_b32_e32 v180, v180, v181, vcc
	v_rsq_f32_e32 v180, v180
	s_nop 0
	v_mul_f32_e32 v181, 0x45800000, v180
	v_cndmask_b32_e32 v180, v180, v181, vcc
	v_mul_f32_e32 v244, 0x3dd53b94, v180
	v_add_u32_e32 v131, 0x6c000, v130
	v_pk_mul_f32 v[46:47], v[46:47], v[244:245] op_sel_hi:[1,0]
	v_pk_mul_f32 v[48:49], v[48:49], v[244:245] op_sel_hi:[1,0]
	v_pk_mul_f32 v[38:39], v[38:39], v[244:245] op_sel_hi:[1,0]
	v_pk_mul_f32 v[40:41], v[40:41], v[244:245] op_sel_hi:[1,0]
	v_cvt_pk_bf16_f32 v172, v46, v47
	v_cvt_pk_bf16_f32 v173, v48, v49
	v_cvt_pk_bf16_f32 v174, v38, v39
	v_cvt_pk_bf16_f32 v175, v40, v41
	global_store_dwordx4 v131, v[172:175], s[12:13]
	v_pk_mul_f32 v[42:43], v[42:43], v[244:245] op_sel_hi:[1,0]
	v_pk_mul_f32 v[44:45], v[44:45], v[244:245] op_sel_hi:[1,0]
	v_pk_mul_f32 v[34:35], v[34:35], v[244:245] op_sel_hi:[1,0]
	v_pk_mul_f32 v[36:37], v[36:37], v[244:245] op_sel_hi:[1,0]
	v_cvt_pk_bf16_f32 v176, v42, v43
	v_cvt_pk_bf16_f32 v177, v44, v45
	v_cvt_pk_bf16_f32 v178, v34, v35
	v_cvt_pk_bf16_f32 v179, v36, v37
	global_store_dwordx4 v131, v[176:179], s[12:13] offset:384
	s_waitcnt vmcnt(14)
	v_pk_add_f32 v[200:201], v[200:201], v[204:205]
	v_pk_add_f32 v[202:203], v[202:203], v[206:207]
	v_add_f32_e32 v180, v200, v201
	v_add_f32_e32 v181, v202, v203
	v_add_f32_e32 v180, v180, v181
	v_fmamk_f32 v180, v180, 0x3b000000, v222
	v_mul_f32_e32 v181, 0x4b800000, v180
	v_cmp_gt_f32_e32 vcc, s92, v180
	s_nop 1
	v_cndmask_b32_e32 v180, v180, v181, vcc
	v_rsq_f32_e32 v180, v180
	s_nop 0
	v_mul_f32_e32 v181, 0x45800000, v180
	v_cndmask_b32_e32 v180, v180, v181, vcc
	v_mul_f32_e32 v244, 0x3dd53b94, v180
	v_add_u32_e32 v131, 0x78000, v130
	v_pk_mul_f32 v[30:31], v[30:31], v[244:245] op_sel_hi:[1,0]
	v_pk_mul_f32 v[32:33], v[32:33], v[244:245] op_sel_hi:[1,0]
	v_pk_mul_f32 v[22:23], v[22:23], v[244:245] op_sel_hi:[1,0]
	v_pk_mul_f32 v[24:25], v[24:25], v[244:245] op_sel_hi:[1,0]
	v_cvt_pk_bf16_f32 v200, v30, v31
	v_cvt_pk_bf16_f32 v201, v32, v33
	v_cvt_pk_bf16_f32 v202, v22, v23
	v_cvt_pk_bf16_f32 v203, v24, v25
	global_store_dwordx4 v131, v[200:203], s[12:13]
	v_pk_mul_f32 v[26:27], v[26:27], v[244:245] op_sel_hi:[1,0]
	v_pk_mul_f32 v[28:29], v[28:29], v[244:245] op_sel_hi:[1,0]
	v_pk_mul_f32 v[18:19], v[18:19], v[244:245] op_sel_hi:[1,0]
	v_pk_mul_f32 v[20:21], v[20:21], v[244:245] op_sel_hi:[1,0]
	v_cvt_pk_bf16_f32 v204, v26, v27
	v_cvt_pk_bf16_f32 v205, v28, v29
	v_cvt_pk_bf16_f32 v206, v18, v19
	v_cvt_pk_bf16_f32 v207, v20, v21
	global_store_dwordx4 v131, v[204:207], s[12:13] offset:384
	s_waitcnt vmcnt(14)
	v_pk_add_f32 v[208:209], v[208:209], v[212:213]
	v_pk_add_f32 v[210:211], v[210:211], v[214:215]
	v_add_f32_e32 v180, v208, v209
	v_add_f32_e32 v181, v210, v211
	v_add_f32_e32 v180, v180, v181
	v_fmamk_f32 v180, v180, 0x3b000000, v222
	v_mul_f32_e32 v181, 0x4b800000, v180
	v_cmp_gt_f32_e32 vcc, s92, v180
	s_nop 1
	v_cndmask_b32_e32 v180, v180, v181, vcc
	v_rsq_f32_e32 v180, v180
	s_nop 0
	v_mul_f32_e32 v181, 0x45800000, v180
	v_cndmask_b32_e32 v180, v180, v181, vcc
	v_mul_f32_e32 v244, 0x3dd53b94, v180
	v_add_u32_e32 v131, 0x84000, v130
	v_pk_mul_f32 v[14:15], v[14:15], v[244:245] op_sel_hi:[1,0]
	v_pk_mul_f32 v[16:17], v[16:17], v[244:245] op_sel_hi:[1,0]
	v_pk_mul_f32 v[6:7], v[6:7], v[244:245] op_sel_hi:[1,0]
	v_pk_mul_f32 v[8:9], v[8:9], v[244:245] op_sel_hi:[1,0]
	v_cvt_pk_bf16_f32 v208, v14, v15
	v_cvt_pk_bf16_f32 v209, v16, v17
	v_cvt_pk_bf16_f32 v210, v6, v7
	v_cvt_pk_bf16_f32 v211, v8, v9
	global_store_dwordx4 v131, v[208:211], s[12:13]
	v_pk_mul_f32 v[10:11], v[10:11], v[244:245] op_sel_hi:[1,0]
	v_pk_mul_f32 v[12:13], v[12:13], v[244:245] op_sel_hi:[1,0]
	v_pk_mul_f32 v[2:3], v[2:3], v[244:245] op_sel_hi:[1,0]
	v_pk_mul_f32 v[4:5], v[4:5], v[244:245] op_sel_hi:[1,0]
	v_cvt_pk_bf16_f32 v212, v10, v11
	v_cvt_pk_bf16_f32 v213, v12, v13
	v_cvt_pk_bf16_f32 v214, v2, v3
	v_cvt_pk_bf16_f32 v215, v4, v5
	global_store_dwordx4 v131, v[212:215], s[12:13] offset:384
	s_setprio 0
	s_branch .LBB0_578

; __device__ __forceinline__ unsigned pk2(float lo, float hi) { f32x2 v = {lo, hi}; bf16x2_t b = __builtin_convertvector(v, bf16x2_t); return __builtin_bit_cast(unsigned, b); }
; __device__ __forceinline__ f32x4 bf_lo4(const u32x4& w) { return (f32x4){__uint_as_float(w[0] << 16), __uint_as_float(w[0] & 0xffff0000u), __uint_as_float(w[1] << 16), __uint_as_float(w[1] & 0xffff0000u)}; }
; __device__ __forceinline__ f32x4 bf_hi4(const u32x4& w) { return (f32x4){__uint_as_float(w[2] << 16), __uint_as_float(w[2] & 0xffff0000u), __uint_as_float(w[3] << 16), __uint_as_float(w[3] & 0xffff0000u)}; }
; __device__ __forceinline__ void epi_resid(bf16_t* XB, float* SS, float alpha, const f32x4 (&acc)[2][2][4][2], const Unit& u, int wr, int wc, int fr, int fq) {
;     const int c0 = u.pn * 256 + wc * 32 + fq * 8;
;     u32x4 pre[2][2];
;     { const bf16_t* p = XB + (size_t)opaque(EPI_ROW(0)) * DM + c0; pre[0][0] = *(const u32x4*)p; pre[0][1] = *(const u32x4*)(p + 128); }
; #pragma unroll
;     for (int it = 0; it < 8; ++it) {
;         const int ai = it >> 2, m = it & 3; const int r = opaque(EPI_ROW(it));
;         if (it + 1 < 8) { const bf16_t* p = XB + (size_t)opaque(EPI_ROW(it + 1)) * DM + c0; pre[(it + 1) & 1][0] = *(const u32x4*)p; pre[(it + 1) & 1][1] = *(const u32x4*)(p + 128); }
;         float q = 0.f;
; #pragma unroll
;         for (int bj = 0; bj < 2; ++bj) {
;             const size_t off = (size_t)r * DM + c0 + bj * 128;
;             const u32x4 bw = pre[it & 1][bj];
;             const f32x4 o0 = bf_lo4(bw) + acc[ai][bj][m][0] * alpha, o1 = bf_hi4(bw) + acc[ai][bj][m][1] * alpha;
;             u32x4 w; w[0] = pk2(o0[0], o0[1]); w[1] = pk2(o0[2], o0[3]); w[2] = pk2(o1[0], o1[1]); w[3] = pk2(o1[2], o1[3]);
;             *(u32x4*)(XB + off) = w;
;             q += (o0[0] * o0[0] + o0[1] * o0[1]) + (o0[2] * o0[2] + o0[3] * o0[3]) + (o1[0] * o1[0] + o1[1] * o1[1]) + (o1[2] * o1[2] + o1[3] * o1[3]);
;         }
.LBB0_733:
	s_andn2_b64 vcc, exec, s[2:3]
	s_cbranch_vccnz .LBB0_754
	s_cmp_gt_i32 s88, 0
	s_mov_b64 s[2:3], -1
	s_cbranch_scc0 .LBB0_752
	s_mov_b64 s[2:3], s[96:97]
	s_add_u32 s12, s2, 0x13800000
	s_addc_u32 s13, s3, 0
	s_add_u32 s2, s2, 0x17800000
	s_addc_u32 s3, s3, 0
	s_lshl_b32 s14, s81, 8
	s_waitcnt lgkmcnt(0)
	v_add_u32_e32 v130, s14, v193
	v_readlane_b32 s14, v254, 34
	v_readlane_b32 s15, v254, 35
	s_and_b64 vcc, exec, s[14:15]
	s_cbranch_vccz .Lrs_noprio
	s_setprio 1
.Lrs_noprio:
	v_lshl_or_b32 v131, s77, 8, v194
	v_lshlrev_b32_e32 v180, 7, v130
	v_lshlrev_b32_e32 v130, 12, v130
	v_lshl_add_u32 v130, v131, 1, v130
	v_readlane_b32 s18, v254, 30
	s_lshl_b32 s16, s77, 4
	s_lshl_b32 s18, s18, 2
	s_add_i32 s16, s16, s18
	s_addk_i32 s16, 0x1000
	v_add_u32_e32 v180, s16, v180
	v_add_u32_e32 v181, 0x4000, v180
	v_xor_b32_e32 v214, 16, v228
	v_xor_b32_e32 v215, 32, v228
	v_lshlrev_b32_e32 v214, 2, v214
	v_lshlrev_b32_e32 v215, 2, v215
	global_load_dwordx4 v[132:135], v130, s[12:13]
	global_load_dwordx4 v[136:139], v130, s[12:13] offset:256
	v_add_u32_e32 v131, 0x10000, v130
	global_load_dwordx4 v[140:143], v131, s[12:13]
	global_load_dwordx4 v[144:147], v131, s[12:13] offset:256
	v_add_u32_e32 v131, 0x20000, v130
	global_load_dwordx4 v[148:151], v131, s[12:13]
	global_load_dwordx4 v[152:155], v131, s[12:13] offset:256
	v_add_u32_e32 v131, 0x30000, v130
	global_load_dwordx4 v[156:159], v131, s[12:13]
	global_load_dwordx4 v[160:163], v131, s[12:13] offset:256
	v_add_u32_e32 v131, 0x80000, v130
	global_load_dwordx4 v[164:167], v131, s[12:13]
	global_load_dwordx4 v[168:171], v131, s[12:13] offset:256
	v_add_u32_e32 v131, 0x90000, v130
	global_load_dwordx4 v[172:175], v131, s[12:13]
	global_load_dwordx4 v[176:179], v131, s[12:13] offset:256
	s_waitcnt vmcnt(10)
	v_lshlrev_b32_e32 v200, 16, v132
	v_and_b32_e32 v201, 0xffff0000, v132
	v_lshlrev_b32_e32 v202, 16, v133
	v_and_b32_e32 v203, 0xffff0000, v133
	v_lshlrev_b32_e32 v204, 16, v134
	v_and_b32_e32 v205, 0xffff0000, v134
	v_lshlrev_b32_e32 v206, 16, v135
	v_and_b32_e32 v207, 0xffff0000, v135
	v_pk_fma_f32 v[126:127], v[126:127], s[40:41], v[200:201]
	v_pk_fma_f32 v[128:129], v[128:129], s[40:41], v[202:203]
	v_pk_fma_f32 v[118:119], v[118:119], s[40:41], v[204:205]
	v_pk_fma_f32 v[120:121], v[120:121], s[40:41], v[206:207]
	v_cvt_pk_bf16_f32 v132, v126, v127
	v_cvt_pk_bf16_f32 v133, v128, v129
	v_cvt_pk_bf16_f32 v134, v118, v119
	v_cvt_pk_bf16_f32 v135, v120, v121
	v_pk_mul_f32 v[208:209], v[126:127], v[126:127]
	v_pk_fma_f32 v[208:209], v[128:129], v[128:129], v[208:209]
	v_pk_fma_f32 v[208:209], v[118:119], v[118:119], v[208:209]
	v_pk_fma_f32 v[208:209], v[120:121], v[120:121], v[208:209]
	global_store_dwordx4 v130, v[132:135], s[12:13]
	v_lshlrev_b32_e32 v200, 16, v136
	v_and_b32_e32 v201, 0xffff0000, v136
	v_lshlrev_b32_e32 v202, 16, v137
	v_and_b32_e32 v203, 0xffff0000, v137
	v_lshlrev_b32_e32 v204, 16, v138
	v_and_b32_e32 v205, 0xffff0000, v138
	v_lshlrev_b32_e32 v206, 16, v139
	v_and_b32_e32 v207, 0xffff0000, v139
	v_pk_fma_f32 v[122:123], v[122:123], s[40:41], v[200:201]
	v_pk_fma_f32 v[124:125], v[124:125], s[40:41], v[202:203]
	v_pk_fma_f32 v[114:115], v[114:115], s[40:41], v[204:205]
	v_pk_fma_f32 v[116:117], v[116:117], s[40:41], v[206:207]
	v_cvt_pk_bf16_f32 v136, v122, v123
	v_cvt_pk_bf16_f32 v137, v124, v125
	v_cvt_pk_bf16_f32 v138, v114, v115
	v_cvt_pk_bf16_f32 v139, v116, v117
	v_pk_fma_f32 v[208:209], v[122:123], v[122:123], v[208:209]
	v_pk_fma_f32 v[208:209], v[124:125], v[124:125], v[208:209]
	v_pk_fma_f32 v[208:209], v[114:115], v[114:115], v[208:209]
	v_pk_fma_f32 v[208:209], v[116:117], v[116:117], v[208:209]
	global_store_dwordx4 v130, v[136:139], s[12:13] offset:256
	v_add_f32_e32 v244, v208, v209
	v_add_u32_e32 v131, 0xa0000, v130
	global_load_dwordx4 v[126:129], v131, s[12:13]
	global_load_dwordx4 v[122:125], v131, s[12:13] offset:256
	v_add_u32_e32 v131, 0xb0000, v130
	global_load_dwordx4 v[118:121], v131, s[12:13]
	global_load_dwordx4 v[114:117], v131, s[12:13] offset:256
	s_waitcnt vmcnt(14)
	v_lshlrev_b32_e32 v200, 16, v140
	v_and_b32_e32 v201, 0xffff0000, v140
	v_lshlrev_b32_e32 v202, 16, v141
	v_and_b32_e32 v203, 0xffff0000, v141
	v_lshlrev_b32_e32 v204, 16, v142
	v_and_b32_e32 v205, 0xffff0000, v142
	v_lshlrev_b32_e32 v206, 16, v143
	v_and_b32_e32 v207, 0xffff0000, v143
	v_pk_fma_f32 v[110:111], v[110:111], s[40:41], v[200:201]
	v_pk_fma_f32 v[112:113], v[112:113], s[40:41], v[202:203]
	v_pk_fma_f32 v[102:103], v[102:103], s[40:41], v[204:205]
	v_pk_fma_f32 v[104:105], v[104:105], s[40:41], v[206:207]
	v_cvt_pk_bf16_f32 v140, v110, v111
	v_cvt_pk_bf16_f32 v141, v112, v113
	v_cvt_pk_bf16_f32 v142, v102, v103
	v_cvt_pk_bf16_f32 v143, v104, v105
	v_pk_mul_f32 v[208:209], v[110:111], v[110:111]
	v_pk_fma_f32 v[208:209], v[112:113], v[112:113], v[208:209]
	v_pk_fma_f32 v[208:209], v[102:103], v[102:103], v[208:209]
	v_pk_fma_f32 v[208:209], v[104:105], v[104:105], v[208:209]
	v_add_u32_e32 v131, 0x10000, v130
	global_store_dwordx4 v131, v[140:143], s[12:13]
	v_lshlrev_b32_e32 v200, 16, v144
	v_and_b32_e32 v201, 0xffff0000, v144
	v_lshlrev_b32_e32 v202, 16, v145
	v_and_b32_e32 v203, 0xffff0000, v145
	v_lshlrev_b32_e32 v204, 16, v146
	v_and_b32_e32 v205, 0xffff0000, v146
	v_lshlrev_b32_e32 v206, 16, v147
	v_and_b32_e32 v207, 0xffff0000, v147
	v_pk_fma_f32 v[106:107], v[106:107], s[40:41], v[200:201]
	v_pk_fma_f32 v[108:109], v[108:109], s[40:41], v[202:203]
	v_pk_fma_f32 v[98:99], v[98:99], s[40:41], v[204:205]
	v_pk_fma_f32 v[100:101], v[100:101], s[40:41], v[206:207]
	v_cvt_pk_bf16_f32 v144, v106, v107
	v_cvt_pk_bf16_f32 v145, v108, v109
	v_cvt_pk_bf16_f32 v146, v98, v99
	v_cvt_pk_bf16_f32 v147, v100, v101
	v_pk_fma_f32 v[208:209], v[106:107], v[106:107], v[208:209]
	v_pk_fma_f32 v[208:209], v[108:109], v[108:109], v[208:209]
	v_pk_fma_f32 v[208:209], v[98:99], v[98:99], v[208:209]
	v_pk_fma_f32 v[208:209], v[100:101], v[100:101], v[208:209]
	global_store_dwordx4 v131, v[144:147], s[12:13] offset:256
	v_add_f32_e32 v245, v208, v209
	s_waitcnt vmcnt(14)
; __device__ __forceinline__ unsigned pk2(float lo, float hi) { f32x2 v = {lo, hi}; bf16x2_t b = __builtin_convertvector(v, bf16x2_t); return __builtin_bit_cast(unsigned, b); }
; __device__ __forceinline__ f32x4 bf_lo4(const u32x4& w) { return (f32x4){__uint_as_float(w[0] << 16), __uint_as_float(w[0] & 0xffff0000u), __uint_as_float(w[1] << 16), __uint_as_float(w[1] & 0xffff0000u)}; }
; __device__ __forceinline__ f32x4 bf_hi4(const u32x4& w) { return (f32x4){__uint_as_float(w[2] << 16), __uint_as_float(w[2] & 0xffff0000u), __uint_as_float(w[3] << 16), __uint_as_float(w[3] & 0xffff0000u)}; }
; __device__ __forceinline__ void epi_resid(bf16_t* XB, float* SS, float alpha, const f32x4 (&acc)[2][2][4][2], const Unit& u, int wr, int wc, int fr, int fq) {
;     ...
;     for (int it = 0; it < 8; ++it) {
;         const int ai = it >> 2, m = it & 3; const int r = opaque(EPI_ROW(it));
;         if (it + 1 < 8) { const bf16_t* p = XB + (size_t)opaque(EPI_ROW(it + 1)) * DM + c0; pre[(it + 1) & 1][0] = *(const u32x4*)p; pre[(it + 1) & 1][1] = *(const u32x4*)(p + 128); }
;         float q = 0.f;
; #pragma unroll
;         for (int bj = 0; bj < 2; ++bj) {
;             const size_t off = (size_t)r * DM + c0 + bj * 128;
;             const u32x4 bw = pre[it & 1][bj];
;             const f32x4 o0 = bf_lo4(bw) + acc[ai][bj][m][0] * alpha, o1 = bf_hi4(bw) + acc[ai][bj][m][1] * alpha;
;             u32x4 w; w[0] = pk2(o0[0], o0[1]); w[1] = pk2(o0[2], o0[3]); w[2] = pk2(o1[0], o1[1]); w[3] = pk2(o1[2], o1[3]);
;             *(u32x4*)(XB + off) = w;
;             q += (o0[0] * o0[0] + o0[1] * o0[1]) + (o0[2] * o0[2] + o0[3] * o0[3]) + (o1[0] * o1[0] + o1[1] * o1[1]) + (o1[2] * o1[2] + o1[3] * o1[3]);
;         }
	v_lshlrev_b32_e32 v200, 16, v148
	v_and_b32_e32 v201, 0xffff0000, v148
	v_lshlrev_b32_e32 v202, 16, v149
	v_and_b32_e32 v203, 0xffff0000, v149
	v_lshlrev_b32_e32 v204, 16, v150
	v_and_b32_e32 v205, 0xffff0000, v150
	v_lshlrev_b32_e32 v206, 16, v151
	v_and_b32_e32 v207, 0xffff0000, v151
	v_pk_fma_f32 v[94:95], v[94:95], s[40:41], v[200:201]
	v_pk_fma_f32 v[96:97], v[96:97], s[40:41], v[202:203]
	v_pk_fma_f32 v[86:87], v[86:87], s[40:41], v[204:205]
	v_pk_fma_f32 v[88:89], v[88:89], s[40:41], v[206:207]
	v_cvt_pk_bf16_f32 v148, v94, v95
	v_cvt_pk_bf16_f32 v149, v96, v97
	v_cvt_pk_bf16_f32 v150, v86, v87
	v_cvt_pk_bf16_f32 v151, v88, v89
	v_pk_mul_f32 v[208:209], v[94:95], v[94:95]
	v_pk_fma_f32 v[208:209], v[96:97], v[96:97], v[208:209]
	v_pk_fma_f32 v[208:209], v[86:87], v[86:87], v[208:209]
	v_pk_fma_f32 v[208:209], v[88:89], v[88:89], v[208:209]
	v_add_u32_e32 v131, 0x20000, v130
	global_store_dwordx4 v131, v[148:151], s[12:13]
	v_lshlrev_b32_e32 v200, 16, v152
	v_and_b32_e32 v201, 0xffff0000, v152
	v_lshlrev_b32_e32 v202, 16, v153
	v_and_b32_e32 v203, 0xffff0000, v153
	v_lshlrev_b32_e32 v204, 16, v154
	v_and_b32_e32 v205, 0xffff0000, v154
	v_lshlrev_b32_e32 v206, 16, v155
	v_and_b32_e32 v207, 0xffff0000, v155
	v_pk_fma_f32 v[90:91], v[90:91], s[40:41], v[200:201]
	v_pk_fma_f32 v[92:93], v[92:93], s[40:41], v[202:203]
	v_pk_fma_f32 v[82:83], v[82:83], s[40:41], v[204:205]
	v_pk_fma_f32 v[84:85], v[84:85], s[40:41], v[206:207]
	v_cvt_pk_bf16_f32 v152, v90, v91
	v_cvt_pk_bf16_f32 v153, v92, v93
	v_cvt_pk_bf16_f32 v154, v82, v83
	v_cvt_pk_bf16_f32 v155, v84, v85
	v_pk_fma_f32 v[208:209], v[90:91], v[90:91], v[208:209]
	v_pk_fma_f32 v[208:209], v[92:93], v[92:93], v[208:209]
	v_pk_fma_f32 v[208:209], v[82:83], v[82:83], v[208:209]
	v_pk_fma_f32 v[208:209], v[84:85], v[84:85], v[208:209]
	global_store_dwordx4 v131, v[152:155], s[12:13] offset:256
	v_add_f32_e32 v246, v208, v209
	s_waitcnt vmcnt(14)
	v_lshlrev_b32_e32 v200, 16, v156
	v_and_b32_e32 v201, 0xffff0000, v156
	v_lshlrev_b32_e32 v202, 16, v157
	v_and_b32_e32 v203, 0xffff0000, v157
	v_lshlrev_b32_e32 v204, 16, v158
	v_and_b32_e32 v205, 0xffff0000, v158
	v_lshlrev_b32_e32 v206, 16, v159
	v_and_b32_e32 v207, 0xffff0000, v159
	v_pk_fma_f32 v[78:79], v[78:79], s[40:41], v[200:201]
	v_pk_fma_f32 v[80:81], v[80:81], s[40:41], v[202:203]
	v_pk_fma_f32 v[70:71], v[70:71], s[40:41], v[204:205]
	v_pk_fma_f32 v[72:73], v[72:73], s[40:41], v[206:207]
	v_cvt_pk_bf16_f32 v156, v78, v79
	v_cvt_pk_bf16_f32 v157, v80, v81
	v_cvt_pk_bf16_f32 v158, v70, v71
	v_cvt_pk_bf16_f32 v159, v72, v73
	v_pk_mul_f32 v[208:209], v[78:79], v[78:79]
	v_pk_fma_f32 v[208:209], v[80:81], v[80:81], v[208:209]
	v_pk_fma_f32 v[208:209], v[70:71], v[70:71], v[208:209]
	v_pk_fma_f32 v[208:209], v[72:73], v[72:73], v[208:209]
	v_add_u32_e32 v131, 0x30000, v130
	global_store_dwordx4 v131, v[156:159], s[12:13]
	v_lshlrev_b32_e32 v200, 16, v160
	v_and_b32_e32 v201, 0xffff0000, v160
	v_lshlrev_b32_e32 v202, 16, v161
	v_and_b32_e32 v203, 0xffff0000, v161
	v_lshlrev_b32_e32 v204, 16, v162
	v_and_b32_e32 v205, 0xffff0000, v162
	v_lshlrev_b32_e32 v206, 16, v163
	v_and_b32_e32 v207, 0xffff0000, v163
	v_pk_fma_f32 v[74:75], v[74:75], s[40:41], v[200:201]
	v_pk_fma_f32 v[76:77], v[76:77], s[40:41], v[202:203]
	v_pk_fma_f32 v[66:67], v[66:67], s[40:41], v[204:205]
	v_pk_fma_f32 v[68:69], v[68:69], s[40:41], v[206:207]
	v_cvt_pk_bf16_f32 v160, v74, v75
	v_cvt_pk_bf16_f32 v161, v76, v77
	v_cvt_pk_bf16_f32 v162, v66, v67
	v_cvt_pk_bf16_f32 v163, v68, v69
	v_pk_fma_f32 v[208:209], v[74:75], v[74:75], v[208:209]
	v_pk_fma_f32 v[208:209], v[76:77], v[76:77], v[208:209]
	v_pk_fma_f32 v[208:209], v[66:67], v[66:67], v[208:209]
	v_pk_fma_f32 v[208:209], v[68:69], v[68:69], v[208:209]
	global_store_dwordx4 v131, v[160:163], s[12:13] offset:256
	v_add_f32_e32 v247, v208, v209
	s_waitcnt vmcnt(14)
	v_lshlrev_b32_e32 v200, 16, v164
	v_and_b32_e32 v201, 0xffff0000, v164
	v_lshlrev_b32_e32 v202, 16, v165
	v_and_b32_e32 v203, 0xffff0000, v165
	v_lshlrev_b32_e32 v204, 16, v166
	v_and_b32_e32 v205, 0xffff0000, v166
	v_lshlrev_b32_e32 v206, 16, v167
	v_and_b32_e32 v207, 0xffff0000, v167
	v_pk_fma_f32 v[62:63], v[62:63], s[40:41], v[200:201]
	v_pk_fma_f32 v[64:65], v[64:65], s[40:41], v[202:203]
	v_pk_fma_f32 v[54:55], v[54:55], s[40:41], v[204:205]
	v_pk_fma_f32 v[56:57], v[56:57], s[40:41], v[206:207]
	v_cvt_pk_bf16_f32 v164, v62, v63
	v_cvt_pk_bf16_f32 v165, v64, v65
	v_cvt_pk_bf16_f32 v166, v54, v55
	v_cvt_pk_bf16_f32 v167, v56, v57
	v_pk_mul_f32 v[208:209], v[62:63], v[62:63]
	v_pk_fma_f32 v[208:209], v[64:65], v[64:65], v[208:209]
	v_pk_fma_f32 v[208:209], v[54:55], v[54:55], v[208:209]
	v_pk_fma_f32 v[208:209], v[56:57], v[56:57], v[208:209]
	v_add_u32_e32 v131, 0x80000, v130
	global_store_dwordx4 v131, v[164:167], s[12:13]
	v_lshlrev_b32_e32 v200, 16, v168
	v_and_b32_e32 v201, 0xffff0000, v168
	v_lshlrev_b32_e32 v202, 16, v169
	v_and_b32_e32 v203, 0xffff0000, v169
	v_lshlrev_b32_e32 v204, 16, v170
	v_and_b32_e32 v205, 0xffff0000, v170
	v_lshlrev_b32_e32 v206, 16, v171
	v_and_b32_e32 v207, 0xffff0000, v171
	v_pk_fma_f32 v[58:59], v[58:59], s[40:41], v[200:201]
	v_pk_fma_f32 v[60:61], v[60:61], s[40:41], v[202:203]
	v_pk_fma_f32 v[50:51], v[50:51], s[40:41], v[204:205]
	v_pk_fma_f32 v[52:53], v[52:53], s[40:41], v[206:207]
	v_cvt_pk_bf16_f32 v168, v58, v59
	v_cvt_pk_bf16_f32 v169, v60, v61
	v_cvt_pk_bf16_f32 v170, v50, v51
	v_cvt_pk_bf16_f32 v171, v52, v53
	v_pk_fma_f32 v[208:209], v[58:59], v[58:59], v[208:209]
	v_pk_fma_f32 v[208:209], v[60:61], v[60:61], v[208:209]
	v_pk_fma_f32 v[208:209], v[50:51], v[50:51], v[208:209]
	v_pk_fma_f32 v[208:209], v[52:53], v[52:53], v[208:209]
	global_store_dwordx4 v131, v[168:171], s[12:13] offset:256
	v_add_f32_e32 v210, v208, v209
	s_waitcnt vmcnt(14)
; __device__ __forceinline__ unsigned pk2(float lo, float hi) { f32x2 v = {lo, hi}; bf16x2_t b = __builtin_convertvector(v, bf16x2_t); return __builtin_bit_cast(unsigned, b); }
; __device__ __forceinline__ f32x4 bf_lo4(const u32x4& w) { return (f32x4){__uint_as_float(w[0] << 16), __uint_as_float(w[0] & 0xffff0000u), __uint_as_float(w[1] << 16), __uint_as_float(w[1] & 0xffff0000u)}; }
; __device__ __forceinline__ f32x4 bf_hi4(const u32x4& w) { return (f32x4){__uint_as_float(w[2] << 16), __uint_as_float(w[2] & 0xffff0000u), __uint_as_float(w[3] << 16), __uint_as_float(w[3] & 0xffff0000u)}; }
; __device__ __forceinline__ void epi_resid(bf16_t* XB, float* SS, float alpha, const f32x4 (&acc)[2][2][4][2], const Unit& u, int wr, int wc, int fr, int fq) {
;     ...
;     for (int it = 0; it < 8; ++it) {
;         const int ai = it >> 2, m = it & 3; const int r = opaque(EPI_ROW(it));
;         if (it + 1 < 8) { const bf16_t* p = XB + (size_t)opaque(EPI_ROW(it + 1)) * DM + c0; pre[(it + 1) & 1][0] = *(const u32x4*)p; pre[(it + 1) & 1][1] = *(const u32x4*)(p + 128); }
;         float q = 0.f;
; #pragma unroll
;         for (int bj = 0; bj < 2; ++bj) {
;             const size_t off = (size_t)r * DM + c0 + bj * 128;
;             const u32x4 bw = pre[it & 1][bj];
;             const f32x4 o0 = bf_lo4(bw) + acc[ai][bj][m][0] * alpha, o1 = bf_hi4(bw) + acc[ai][bj][m][1] * alpha;
;             u32x4 w; w[0] = pk2(o0[0], o0[1]); w[1] = pk2(o0[2], o0[3]); w[2] = pk2(o1[0], o1[1]); w[3] = pk2(o1[2], o1[3]);
;             *(u32x4*)(XB + off) = w;
;             q += (o0[0] * o0[0] + o0[1] * o0[1]) + (o0[2] * o0[2] + o0[3] * o0[3]) + (o1[0] * o1[0] + o1[1] * o1[1]) + (o1[2] * o1[2] + o1[3] * o1[3]);
;         }
	v_lshlrev_b32_e32 v200, 16, v172
	v_and_b32_e32 v201, 0xffff0000, v172
	v_lshlrev_b32_e32 v202, 16, v173
	v_and_b32_e32 v203, 0xffff0000, v173
	v_lshlrev_b32_e32 v204, 16, v174
	v_and_b32_e32 v205, 0xffff0000, v174
	v_lshlrev_b32_e32 v206, 16, v175
	v_and_b32_e32 v207, 0xffff0000, v175
	v_pk_fma_f32 v[46:47], v[46:47], s[40:41], v[200:201]
	v_pk_fma_f32 v[48:49], v[48:49], s[40:41], v[202:203]
	v_pk_fma_f32 v[38:39], v[38:39], s[40:41], v[204:205]
	v_pk_fma_f32 v[40:41], v[40:41], s[40:41], v[206:207]
	v_cvt_pk_bf16_f32 v172, v46, v47
	v_cvt_pk_bf16_f32 v173, v48, v49
	v_cvt_pk_bf16_f32 v174, v38, v39
	v_cvt_pk_bf16_f32 v175, v40, v41
	v_pk_mul_f32 v[208:209], v[46:47], v[46:47]
	v_pk_fma_f32 v[208:209], v[48:49], v[48:49], v[208:209]
	v_pk_fma_f32 v[208:209], v[38:39], v[38:39], v[208:209]
	v_pk_fma_f32 v[208:209], v[40:41], v[40:41], v[208:209]
	v_add_u32_e32 v131, 0x90000, v130
	global_store_dwordx4 v131, v[172:175], s[12:13]
	v_lshlrev_b32_e32 v200, 16, v176
	v_and_b32_e32 v201, 0xffff0000, v176
	v_lshlrev_b32_e32 v202, 16, v177
	v_and_b32_e32 v203, 0xffff0000, v177
	v_lshlrev_b32_e32 v204, 16, v178
	v_and_b32_e32 v205, 0xffff0000, v178
	v_lshlrev_b32_e32 v206, 16, v179
	v_and_b32_e32 v207, 0xffff0000, v179
	v_pk_fma_f32 v[42:43], v[42:43], s[40:41], v[200:201]
	v_pk_fma_f32 v[44:45], v[44:45], s[40:41], v[202:203]
	v_pk_fma_f32 v[34:35], v[34:35], s[40:41], v[204:205]
	v_pk_fma_f32 v[36:37], v[36:37], s[40:41], v[206:207]
	v_cvt_pk_bf16_f32 v176, v42, v43
	v_cvt_pk_bf16_f32 v177, v44, v45
	v_cvt_pk_bf16_f32 v178, v34, v35
	v_cvt_pk_bf16_f32 v179, v36, v37
	v_pk_fma_f32 v[208:209], v[42:43], v[42:43], v[208:209]
	v_pk_fma_f32 v[208:209], v[44:45], v[44:45], v[208:209]
	v_pk_fma_f32 v[208:209], v[34:35], v[34:35], v[208:209]
	v_pk_fma_f32 v[208:209], v[36:37], v[36:37], v[208:209]
	global_store_dwordx4 v131, v[176:179], s[12:13] offset:256
	v_add_f32_e32 v211, v208, v209
	s_waitcnt vmcnt(12)
	v_lshlrev_b32_e32 v200, 16, v126
	v_and_b32_e32 v201, 0xffff0000, v126
	v_lshlrev_b32_e32 v202, 16, v127
	v_and_b32_e32 v203, 0xffff0000, v127
	v_lshlrev_b32_e32 v204, 16, v128
	v_and_b32_e32 v205, 0xffff0000, v128
	v_lshlrev_b32_e32 v206, 16, v129
	v_and_b32_e32 v207, 0xffff0000, v129
	v_pk_fma_f32 v[30:31], v[30:31], s[40:41], v[200:201]
	v_pk_fma_f32 v[32:33], v[32:33], s[40:41], v[202:203]
	v_pk_fma_f32 v[22:23], v[22:23], s[40:41], v[204:205]
	v_pk_fma_f32 v[24:25], v[24:25], s[40:41], v[206:207]
	v_cvt_pk_bf16_f32 v126, v30, v31
	v_cvt_pk_bf16_f32 v127, v32, v33
	v_cvt_pk_bf16_f32 v128, v22, v23
	v_cvt_pk_bf16_f32 v129, v24, v25
	v_pk_mul_f32 v[208:209], v[30:31], v[30:31]
	v_pk_fma_f32 v[208:209], v[32:33], v[32:33], v[208:209]
	v_pk_fma_f32 v[208:209], v[22:23], v[22:23], v[208:209]
	v_pk_fma_f32 v[208:209], v[24:25], v[24:25], v[208:209]
	v_add_u32_e32 v131, 0xa0000, v130
	global_store_dwordx4 v131, v[126:129], s[12:13]
	v_lshlrev_b32_e32 v200, 16, v122
	v_and_b32_e32 v201, 0xffff0000, v122
	v_lshlrev_b32_e32 v202, 16, v123
	v_and_b32_e32 v203, 0xffff0000, v123
	v_lshlrev_b32_e32 v204, 16, v124
	v_and_b32_e32 v205, 0xffff0000, v124
	v_lshlrev_b32_e32 v206, 16, v125
	v_and_b32_e32 v207, 0xffff0000, v125
	v_pk_fma_f32 v[26:27], v[26:27], s[40:41], v[200:201]
	v_pk_fma_f32 v[28:29], v[28:29], s[40:41], v[202:203]
	v_pk_fma_f32 v[18:19], v[18:19], s[40:41], v[204:205]
	v_pk_fma_f32 v[20:21], v[20:21], s[40:41], v[206:207]
	v_cvt_pk_bf16_f32 v122, v26, v27
	v_cvt_pk_bf16_f32 v123, v28, v29
	v_cvt_pk_bf16_f32 v124, v18, v19
	v_cvt_pk_bf16_f32 v125, v20, v21
	v_pk_fma_f32 v[208:209], v[26:27], v[26:27], v[208:209]
	v_pk_fma_f32 v[208:209], v[28:29], v[28:29], v[208:209]
	v_pk_fma_f32 v[208:209], v[18:19], v[18:19], v[208:209]
	v_pk_fma_f32 v[208:209], v[20:21], v[20:21], v[208:209]
	global_store_dwordx4 v131, v[122:125], s[12:13] offset:256
	v_add_f32_e32 v212, v208, v209
	s_waitcnt vmcnt(12)
; __device__ __forceinline__ unsigned pk2(float lo, float hi) { f32x2 v = {lo, hi}; bf16x2_t b = __builtin_convertvector(v, bf16x2_t); return __builtin_bit_cast(unsigned, b); }
; __device__ __forceinline__ f32x4 bf_lo4(const u32x4& w) { return (f32x4){__uint_as_float(w[0] << 16), __uint_as_float(w[0] & 0xffff0000u), __uint_as_float(w[1] << 16), __uint_as_float(w[1] & 0xffff0000u)}; }
; __device__ __forceinline__ f32x4 bf_hi4(const u32x4& w) { return (f32x4){__uint_as_float(w[2] << 16), __uint_as_float(w[2] & 0xffff0000u), __uint_as_float(w[3] << 16), __uint_as_float(w[3] & 0xffff0000u)}; }
; __device__ __forceinline__ void epi_resid(bf16_t* XB, float* SS, float alpha, const f32x4 (&acc)[2][2][4][2], const Unit& u, int wr, int wc, int fr, int fq) {
;     ...
;         for (int bj = 0; bj < 2; ++bj) {
;             const size_t off = (size_t)r * DM + c0 + bj * 128;
;             const u32x4 bw = pre[it & 1][bj];
;             const f32x4 o0 = bf_lo4(bw) + acc[ai][bj][m][0] * alpha, o1 = bf_hi4(bw) + acc[ai][bj][m][1] * alpha;
;             u32x4 w; w[0] = pk2(o0[0], o0[1]); w[1] = pk2(o0[2], o0[3]); w[2] = pk2(o1[0], o1[1]); w[3] = pk2(o1[2], o1[3]);
;             *(u32x4*)(XB + off) = w;
;             q += (o0[0] * o0[0] + o0[1] * o0[1]) + (o0[2] * o0[2] + o0[3] * o0[3]) + (o1[0] * o1[0] + o1[1] * o1[1]) + (o1[2] * o1[2] + o1[3] * o1[3]);
;         }
;         q += __shfl_xor(q, 16); q += __shfl_xor(q, 32);
;         if (fq == 0) SS[(size_t)r * 32 + u.pn * 4 + wc] = q;
;         asm volatile("" ::: "memory");
;     }
	v_lshlrev_b32_e32 v200, 16, v118
	v_and_b32_e32 v201, 0xffff0000, v118
	v_lshlrev_b32_e32 v202, 16, v119
	v_and_b32_e32 v203, 0xffff0000, v119
	v_lshlrev_b32_e32 v204, 16, v120
	v_and_b32_e32 v205, 0xffff0000, v120
	v_lshlrev_b32_e32 v206, 16, v121
	v_and_b32_e32 v207, 0xffff0000, v121
	v_pk_fma_f32 v[14:15], v[14:15], s[40:41], v[200:201]
	v_pk_fma_f32 v[16:17], v[16:17], s[40:41], v[202:203]
	v_pk_fma_f32 v[6:7], v[6:7], s[40:41], v[204:205]
	v_pk_fma_f32 v[8:9], v[8:9], s[40:41], v[206:207]
	v_cvt_pk_bf16_f32 v118, v14, v15
	v_cvt_pk_bf16_f32 v119, v16, v17
	v_cvt_pk_bf16_f32 v120, v6, v7
	v_cvt_pk_bf16_f32 v121, v8, v9
	v_pk_mul_f32 v[208:209], v[14:15], v[14:15]
	v_pk_fma_f32 v[208:209], v[16:17], v[16:17], v[208:209]
	v_pk_fma_f32 v[208:209], v[6:7], v[6:7], v[208:209]
	v_pk_fma_f32 v[208:209], v[8:9], v[8:9], v[208:209]
	v_add_u32_e32 v131, 0xb0000, v130
	global_store_dwordx4 v131, v[118:121], s[12:13]
	v_lshlrev_b32_e32 v200, 16, v114
	v_and_b32_e32 v201, 0xffff0000, v114
	v_lshlrev_b32_e32 v202, 16, v115
	v_and_b32_e32 v203, 0xffff0000, v115
	v_lshlrev_b32_e32 v204, 16, v116
	v_and_b32_e32 v205, 0xffff0000, v116
	v_lshlrev_b32_e32 v206, 16, v117
	v_and_b32_e32 v207, 0xffff0000, v117
	v_pk_fma_f32 v[10:11], v[10:11], s[40:41], v[200:201]
	v_pk_fma_f32 v[12:13], v[12:13], s[40:41], v[202:203]
	v_pk_fma_f32 v[2:3], v[2:3], s[40:41], v[204:205]
	v_pk_fma_f32 v[4:5], v[4:5], s[40:41], v[206:207]
	v_cvt_pk_bf16_f32 v114, v10, v11
	v_cvt_pk_bf16_f32 v115, v12, v13
	v_cvt_pk_bf16_f32 v116, v2, v3
	v_cvt_pk_bf16_f32 v117, v4, v5
	v_pk_fma_f32 v[208:209], v[10:11], v[10:11], v[208:209]
	v_pk_fma_f32 v[208:209], v[12:13], v[12:13], v[208:209]
	v_pk_fma_f32 v[208:209], v[2:3], v[2:3], v[208:209]
	v_pk_fma_f32 v[208:209], v[4:5], v[4:5], v[208:209]
	global_store_dwordx4 v131, v[114:117], s[12:13] offset:256
	v_add_f32_e32 v213, v208, v209
	ds_bpermute_b32 v200, v214, v244
	ds_bpermute_b32 v201, v214, v245
	ds_bpermute_b32 v202, v214, v246
	ds_bpermute_b32 v203, v214, v247
	ds_bpermute_b32 v204, v214, v210
	ds_bpermute_b32 v205, v214, v211
	ds_bpermute_b32 v206, v214, v212
	ds_bpermute_b32 v207, v214, v213
	s_waitcnt lgkmcnt(0)
	v_add_f32_e32 v244, v244, v200
	v_add_f32_e32 v245, v245, v201
	v_add_f32_e32 v246, v246, v202
	v_add_f32_e32 v247, v247, v203
	v_add_f32_e32 v210, v210, v204
	v_add_f32_e32 v211, v211, v205
	v_add_f32_e32 v212, v212, v206
	v_add_f32_e32 v213, v213, v207
	ds_bpermute_b32 v200, v215, v244
	ds_bpermute_b32 v201, v215, v245
	ds_bpermute_b32 v202, v215, v246
	ds_bpermute_b32 v203, v215, v247
	ds_bpermute_b32 v204, v215, v210
	ds_bpermute_b32 v205, v215, v211
	ds_bpermute_b32 v206, v215, v212
	ds_bpermute_b32 v207, v215, v213
	s_waitcnt lgkmcnt(0)
	v_add_f32_e32 v244, v244, v200
	v_add_f32_e32 v245, v245, v201
	v_add_f32_e32 v246, v246, v202
	v_add_f32_e32 v247, v247, v203
	v_add_f32_e32 v210, v210, v204
	v_add_f32_e32 v211, v211, v205
	v_add_f32_e32 v212, v212, v206
	v_add_f32_e32 v213, v213, v207
	s_and_saveexec_b64 s[14:15], s[8:9]
	global_store_dword v180, v244, s[2:3] offset:-4096
	global_store_dword v180, v245, s[2:3] offset:-2048
	global_store_dword v180, v246, s[2:3]
	global_store_dword v180, v247, s[2:3] offset:2048
	global_store_dword v181, v210, s[2:3] offset:-4096
	global_store_dword v181, v211, s[2:3] offset:-2048
	global_store_dword v181, v212, s[2:3]
	global_store_dword v181, v213, s[2:3] offset:2048
	s_or_b64 exec, exec, s[14:15]
	s_setprio 0
	s_mov_b64 s[2:3], 0
